# P8 output stores plain (write-back, neither nt nor sc1) together with the plain residual loads: half-line pieces merge in L2
# speedup vs baseline: 1.0104x; 1.0026x over previous
.LBB0_1092:
	v_lshl_or_b32 v128, s47, 8, v166
	v_lshl_add_u32 v160, s46, 8, v164
	s_ashr_i32 s20, s46, 3
	v_ashrrev_i32_e32 v129, 31, v128
	v_ashrrev_i32_e32 v161, 31, v160
	s_mul_hi_i32 s21, s20, 0xc000
	s_mul_i32 s20, s20, 0xc000
	v_lshl_add_u64 v[158:159], v[128:129], 1, s[28:29]
	v_lshlrev_b64 v[130:131], 12, v[160:161]
	s_add_u32 s20, s35, s20
	v_lshl_add_u64 v[130:131], v[158:159], 0, v[130:131]
	v_lshlrev_b64 v[156:157], 2, v[128:129]
	s_addc_u32 s21, s44, s21
	global_load_dwordx2 v[170:171], v[130:131], off
	global_load_dwordx2 v[172:173], v[130:131], off offset:32
	global_load_dwordx2 v[176:177], v[130:131], off offset:288
	v_lshl_add_u64 v[128:129], s[20:21], 0, v[156:157]
	v_or_b32_e32 v178, 16, v160
	global_load_dwordx2 v[174:175], v[130:131], off offset:256
	global_load_dwordx4 v[132:135], v[128:129], off offset:512
	global_load_dwordx4 v[140:143], v[128:129], off
	global_load_dwordx4 v[136:139], v[128:129], off offset:64
	v_ashrrev_i32_e32 v179, 31, v178
	global_load_dwordx4 v[128:131], v[128:129], off offset:576
	v_lshlrev_b64 v[162:163], 12, v[178:179]
	v_lshl_add_u64 v[162:163], v[158:159], 0, v[162:163]
	global_load_dwordx2 v[180:181], v[162:163], off
	global_load_dwordx2 v[182:183], v[162:163], off offset:32
	global_load_dwordx2 v[184:185], v[162:163], off offset:256
	global_load_dwordx2 v[186:187], v[162:163], off offset:288
	v_or_b32_e32 v188, 32, v160
	v_ashrrev_i32_e32 v189, 31, v188
	v_lshlrev_b64 v[162:163], 12, v[188:189]
	v_lshl_add_u64 v[190:191], v[158:159], 0, v[162:163]
	global_load_dwordx2 v[192:193], v[190:191], off
	global_load_dwordx2 v[196:197], v[190:191], off offset:32
	v_or_b32_e32 v162, 48, v160
	v_ashrrev_i32_e32 v163, 31, v162
	v_lshlrev_b64 v[198:199], 12, v[162:163]
	v_lshl_add_u64 v[198:199], v[158:159], 0, v[198:199]
	global_load_dwordx2 v[200:201], v[190:191], off offset:256
	s_nop 0
	global_load_dwordx2 v[190:191], v[190:191], off offset:288
	s_nop 0
	global_load_dwordx2 v[202:203], v[198:199], off
	global_load_dwordx2 v[204:205], v[198:199], off offset:32
	global_load_dwordx2 v[206:207], v[198:199], off offset:256
	s_nop 0
	global_load_dwordx2 v[198:199], v[198:199], off offset:288
	v_lshlrev_b64 v[194:195], 13, v[160:161]
	v_lshl_add_u64 v[194:195], s[6:7], 0, v[194:195]
	v_lshlrev_b64 v[178:179], 13, v[178:179]
	v_lshl_add_u64 v[194:195], v[194:195], 0, v[156:157]
	v_lshl_add_u64 v[178:179], s[6:7], 0, v[178:179]
	v_lshl_add_u64 v[178:179], v[178:179], 0, v[156:157]
	s_and_b64 vcc, exec, s[0:1]
	s_mov_b64 s[0:1], -1
	s_waitcnt vmcnt(0)
	v_lshlrev_b32_e32 v208, 16, v170
	v_and_b32_e32 v209, 0xffff0000, v170
	v_lshlrev_b32_e32 v170, 16, v171
	v_and_b32_e32 v171, 0xffff0000, v171
	v_lshlrev_b32_e32 v210, 16, v172
	v_and_b32_e32 v211, 0xffff0000, v172
	v_lshlrev_b32_e32 v172, 16, v173
	v_and_b32_e32 v173, 0xffff0000, v173
	v_lshlrev_b32_e32 v214, 16, v176
	v_and_b32_e32 v215, 0xffff0000, v176
	v_lshlrev_b32_e32 v176, 16, v177
	v_and_b32_e32 v177, 0xffff0000, v177
	v_lshlrev_b32_e32 v212, 16, v174
	v_and_b32_e32 v213, 0xffff0000, v174
	v_lshlrev_b32_e32 v174, 16, v175
	v_and_b32_e32 v175, 0xffff0000, v175
	v_pk_fma_f32 v[126:127], v[126:127], v[142:143], v[170:171]
	v_pk_fma_f32 v[124:125], v[124:125], v[140:141], v[208:209]
	v_pk_fma_f32 v[122:123], v[122:123], v[138:139], v[172:173]
	v_pk_fma_f32 v[110:111], v[110:111], v[130:131], v[176:177]
	v_pk_fma_f32 v[108:109], v[108:109], v[128:129], v[214:215]
	v_lshlrev_b32_e32 v170, 16, v180
	v_and_b32_e32 v171, 0xffff0000, v180
	v_lshlrev_b32_e32 v172, 16, v181
	v_and_b32_e32 v173, 0xffff0000, v181
	v_pk_fma_f32 v[120:121], v[120:121], v[136:137], v[210:211]
	v_pk_fma_f32 v[114:115], v[114:115], v[134:135], v[174:175]
	v_pk_fma_f32 v[112:113], v[112:113], v[132:133], v[212:213]
	flat_store_dwordx4 v[194:195], v[124:127]
	flat_store_dwordx4 v[194:195], v[120:123] offset:64
	flat_store_dwordx4 v[194:195], v[112:115] offset:512
	flat_store_dwordx4 v[194:195], v[108:111] offset:576
	v_lshlrev_b32_e32 v174, 16, v182
	v_and_b32_e32 v175, 0xffff0000, v182
	v_pk_fma_f32 v[110:111], v[118:119], v[142:143], v[172:173]
	v_pk_fma_f32 v[108:109], v[116:117], v[140:141], v[170:171]
	flat_store_dwordx4 v[178:179], v[108:111]
	v_pk_fma_f32 v[104:105], v[104:105], v[136:137], v[174:175]
	s_nop 0
	v_lshlrev_b32_e32 v108, 16, v183
	v_and_b32_e32 v109, 0xffff0000, v183
	v_pk_fma_f32 v[106:107], v[106:107], v[138:139], v[108:109]
	flat_store_dwordx4 v[178:179], v[104:107] offset:64
	s_nop 1
	v_lshlrev_b32_e32 v104, 16, v184
	v_and_b32_e32 v105, 0xffff0000, v184
	v_lshlrev_b32_e32 v106, 16, v185
	v_and_b32_e32 v107, 0xffff0000, v185
	v_pk_fma_f32 v[102:103], v[102:103], v[134:135], v[106:107]
	v_pk_fma_f32 v[100:101], v[100:101], v[132:133], v[104:105]
	flat_store_dwordx4 v[178:179], v[100:103] offset:512
	s_nop 1
	v_lshlrev_b32_e32 v100, 16, v186
	v_and_b32_e32 v101, 0xffff0000, v186
	v_lshlrev_b32_e32 v102, 16, v187
	v_and_b32_e32 v103, 0xffff0000, v187
	v_pk_fma_f32 v[94:95], v[94:95], v[130:131], v[102:103]
	v_pk_fma_f32 v[92:93], v[92:93], v[128:129], v[100:101]
	flat_store_dwordx4 v[178:179], v[92:95] offset:576
	s_nop 1
	v_lshlrev_b32_e32 v92, 16, v192
	v_and_b32_e32 v93, 0xffff0000, v192
	v_pk_fma_f32 v[92:93], v[96:97], v[140:141], v[92:93]
	v_lshlrev_b64 v[96:97], 13, v[188:189]
	v_lshlrev_b32_e32 v94, 16, v193
	v_and_b32_e32 v95, 0xffff0000, v193
	v_lshl_add_u64 v[96:97], s[6:7], 0, v[96:97]
	v_pk_fma_f32 v[94:95], v[98:99], v[142:143], v[94:95]
	v_lshl_add_u64 v[96:97], v[96:97], 0, v[156:157]
	flat_store_dwordx4 v[96:97], v[92:95]
	v_add_u32_e32 v98, 0xb0, v160
	v_ashrrev_i32_e32 v99, 31, v98
	v_lshlrev_b32_e32 v92, 16, v196
	v_and_b32_e32 v93, 0xffff0000, v196
	v_lshlrev_b32_e32 v94, 16, v197
	v_and_b32_e32 v95, 0xffff0000, v197
	v_pk_fma_f32 v[90:91], v[90:91], v[138:139], v[94:95]
	v_pk_fma_f32 v[88:89], v[88:89], v[136:137], v[92:93]
	flat_store_dwordx4 v[96:97], v[88:91] offset:64
	s_nop 1
	v_lshlrev_b32_e32 v88, 16, v200
	v_and_b32_e32 v89, 0xffff0000, v200
	v_lshlrev_b32_e32 v90, 16, v201
	v_and_b32_e32 v91, 0xffff0000, v201
	v_pk_fma_f32 v[86:87], v[86:87], v[134:135], v[90:91]
	v_pk_fma_f32 v[84:85], v[84:85], v[132:133], v[88:89]
	flat_store_dwordx4 v[96:97], v[84:87] offset:512
	v_add_u32_e32 v88, 0xa0, v160
	v_ashrrev_i32_e32 v89, 31, v88
	v_lshlrev_b32_e32 v84, 16, v190
	v_and_b32_e32 v85, 0xffff0000, v190
	v_lshlrev_b32_e32 v86, 16, v191
	v_and_b32_e32 v87, 0xffff0000, v191
	v_pk_fma_f32 v[78:79], v[78:79], v[130:131], v[86:87]
	v_pk_fma_f32 v[76:77], v[76:77], v[128:129], v[84:85]
	flat_store_dwordx4 v[96:97], v[76:79] offset:576
	s_nop 1
	v_lshlrev_b32_e32 v76, 16, v202
	v_and_b32_e32 v77, 0xffff0000, v202
	v_pk_fma_f32 v[76:77], v[80:81], v[140:141], v[76:77]
	v_lshlrev_b64 v[80:81], 13, v[162:163]
	v_lshlrev_b32_e32 v78, 16, v203
	v_and_b32_e32 v79, 0xffff0000, v203
	v_lshl_add_u64 v[80:81], s[6:7], 0, v[80:81]
	v_pk_fma_f32 v[78:79], v[82:83], v[142:143], v[78:79]
	v_lshl_add_u64 v[80:81], v[80:81], 0, v[156:157]
	flat_store_dwordx4 v[80:81], v[76:79]
	s_nop 1
	v_lshlrev_b32_e32 v76, 16, v204
	v_and_b32_e32 v77, 0xffff0000, v204
	v_lshlrev_b32_e32 v78, 16, v205
	v_and_b32_e32 v79, 0xffff0000, v205
	v_pk_fma_f32 v[74:75], v[74:75], v[138:139], v[78:79]
	v_pk_fma_f32 v[72:73], v[72:73], v[136:137], v[76:77]
	flat_store_dwordx4 v[80:81], v[72:75] offset:64
	v_add_u32_e32 v78, 0x90, v160
	v_ashrrev_i32_e32 v79, 31, v78
	v_lshlrev_b32_e32 v72, 16, v206
	v_and_b32_e32 v73, 0xffff0000, v206
	v_lshlrev_b32_e32 v74, 16, v207
	v_and_b32_e32 v75, 0xffff0000, v207
	v_pk_fma_f32 v[70:71], v[70:71], v[134:135], v[74:75]
	v_pk_fma_f32 v[68:69], v[68:69], v[132:133], v[72:73]
	flat_store_dwordx4 v[80:81], v[68:71] offset:512
	s_nop 1
	v_lshlrev_b32_e32 v68, 16, v198
	v_and_b32_e32 v69, 0xffff0000, v198
	v_lshlrev_b32_e32 v70, 16, v199
	v_and_b32_e32 v71, 0xffff0000, v199
	v_pk_fma_f32 v[64:65], v[64:65], v[128:129], v[68:69]
	v_add_u32_e32 v68, 0x80, v160
	v_pk_fma_f32 v[66:67], v[66:67], v[130:131], v[70:71]
	v_ashrrev_i32_e32 v69, 31, v68
	flat_store_dwordx4 v[80:81], v[64:67] offset:576
	s_nop 1
	v_lshlrev_b64 v[64:65], 12, v[68:69]
	v_lshl_add_u64 v[64:65], v[158:159], 0, v[64:65]
	global_load_dwordx2 v[70:71], v[64:65], off
	global_load_dwordx2 v[72:73], v[64:65], off offset:32
	global_load_dwordx2 v[74:75], v[64:65], off offset:256
	global_load_dwordx2 v[76:77], v[64:65], off offset:288
	v_lshlrev_b64 v[64:65], 12, v[78:79]
	v_lshl_add_u64 v[64:65], v[158:159], 0, v[64:65]
	global_load_dwordx2 v[80:81], v[64:65], off
	global_load_dwordx2 v[82:83], v[64:65], off offset:32
	global_load_dwordx2 v[84:85], v[64:65], off offset:256
	global_load_dwordx2 v[86:87], v[64:65], off offset:288
	v_lshlrev_b64 v[64:65], 12, v[88:89]
	v_lshl_add_u64 v[64:65], v[158:159], 0, v[64:65]
	global_load_dwordx2 v[90:91], v[64:65], off
	global_load_dwordx2 v[92:93], v[64:65], off offset:32
	global_load_dwordx2 v[94:95], v[64:65], off offset:256
	global_load_dwordx2 v[96:97], v[64:65], off offset:288
	v_lshlrev_b64 v[64:65], 12, v[98:99]
	v_lshl_add_u64 v[64:65], v[158:159], 0, v[64:65]
	global_load_dwordx2 v[100:101], v[64:65], off
	global_load_dwordx2 v[102:103], v[64:65], off offset:32
	global_load_dwordx2 v[66:67], v[64:65], off offset:256
	s_nop 0
	global_load_dwordx2 v[64:65], v[64:65], off offset:288
	v_lshlrev_b64 v[68:69], 13, v[68:69]
	v_lshl_add_u64 v[68:69], s[6:7], 0, v[68:69]
	v_lshl_add_u64 v[68:69], v[68:69], 0, v[156:157]
	s_waitcnt vmcnt(0)
	v_lshlrev_b32_e32 v104, 16, v70
	v_and_b32_e32 v105, 0xffff0000, v70
	v_lshlrev_b32_e32 v70, 16, v71
	v_and_b32_e32 v71, 0xffff0000, v71
	v_pk_fma_f32 v[62:63], v[62:63], v[142:143], v[70:71]
	v_pk_fma_f32 v[60:61], v[60:61], v[140:141], v[104:105]
	flat_store_dwordx4 v[68:69], v[60:63]
	s_nop 1
	v_lshlrev_b32_e32 v60, 16, v72
	v_and_b32_e32 v61, 0xffff0000, v72
	v_lshlrev_b32_e32 v62, 16, v73
	v_and_b32_e32 v63, 0xffff0000, v73
	v_pk_fma_f32 v[58:59], v[58:59], v[138:139], v[62:63]
	v_pk_fma_f32 v[56:57], v[56:57], v[136:137], v[60:61]
	flat_store_dwordx4 v[68:69], v[56:59] offset:64
	s_nop 1
	v_lshlrev_b32_e32 v56, 16, v74
	v_and_b32_e32 v57, 0xffff0000, v74
	v_lshlrev_b32_e32 v58, 16, v75
	v_and_b32_e32 v59, 0xffff0000, v75
	v_pk_fma_f32 v[54:55], v[54:55], v[134:135], v[58:59]
	v_pk_fma_f32 v[52:53], v[52:53], v[132:133], v[56:57]
	flat_store_dwordx4 v[68:69], v[52:55] offset:512
	s_nop 1
	v_lshlrev_b32_e32 v52, 16, v76
	v_and_b32_e32 v53, 0xffff0000, v76
	v_lshlrev_b32_e32 v54, 16, v77
	v_and_b32_e32 v55, 0xffff0000, v77
	v_pk_fma_f32 v[46:47], v[46:47], v[130:131], v[54:55]
	v_pk_fma_f32 v[44:45], v[44:45], v[128:129], v[52:53]
	flat_store_dwordx4 v[68:69], v[44:47] offset:576
	s_nop 1
	v_lshlrev_b32_e32 v44, 16, v80
	v_and_b32_e32 v45, 0xffff0000, v80
	v_pk_fma_f32 v[44:45], v[48:49], v[140:141], v[44:45]
	v_lshlrev_b64 v[48:49], 13, v[78:79]
	v_lshlrev_b32_e32 v46, 16, v81
	v_and_b32_e32 v47, 0xffff0000, v81
	v_lshl_add_u64 v[48:49], s[6:7], 0, v[48:49]
	v_pk_fma_f32 v[46:47], v[50:51], v[142:143], v[46:47]
	v_lshl_add_u64 v[48:49], v[48:49], 0, v[156:157]
	flat_store_dwordx4 v[48:49], v[44:47]
	s_nop 1
	v_lshlrev_b32_e32 v44, 16, v82
	v_and_b32_e32 v45, 0xffff0000, v82
	v_lshlrev_b32_e32 v46, 16, v83
	v_and_b32_e32 v47, 0xffff0000, v83
	v_pk_fma_f32 v[42:43], v[42:43], v[138:139], v[46:47]
	v_pk_fma_f32 v[40:41], v[40:41], v[136:137], v[44:45]
	flat_store_dwordx4 v[48:49], v[40:43] offset:64
	s_nop 1
	v_lshlrev_b32_e32 v40, 16, v84
	v_and_b32_e32 v41, 0xffff0000, v84
	v_lshlrev_b32_e32 v42, 16, v85
	v_and_b32_e32 v43, 0xffff0000, v85
	v_pk_fma_f32 v[38:39], v[38:39], v[134:135], v[42:43]
	v_pk_fma_f32 v[36:37], v[36:37], v[132:133], v[40:41]
	flat_store_dwordx4 v[48:49], v[36:39] offset:512
	s_nop 1
	v_lshlrev_b32_e32 v36, 16, v86
	v_and_b32_e32 v37, 0xffff0000, v86
	v_lshlrev_b32_e32 v38, 16, v87
	v_and_b32_e32 v39, 0xffff0000, v87
	v_pk_fma_f32 v[30:31], v[30:31], v[130:131], v[38:39]
	v_pk_fma_f32 v[28:29], v[28:29], v[128:129], v[36:37]
	flat_store_dwordx4 v[48:49], v[28:31] offset:576
	s_nop 1
	v_lshlrev_b32_e32 v28, 16, v90
	v_and_b32_e32 v29, 0xffff0000, v90
	v_pk_fma_f32 v[28:29], v[32:33], v[140:141], v[28:29]
	v_lshlrev_b64 v[32:33], 13, v[88:89]
	v_lshlrev_b32_e32 v30, 16, v91
	v_and_b32_e32 v31, 0xffff0000, v91
	v_lshl_add_u64 v[32:33], s[6:7], 0, v[32:33]
	v_pk_fma_f32 v[30:31], v[34:35], v[142:143], v[30:31]
	v_lshl_add_u64 v[32:33], v[32:33], 0, v[156:157]
	flat_store_dwordx4 v[32:33], v[28:31]
	s_nop 1
	v_lshlrev_b32_e32 v28, 16, v92
	v_and_b32_e32 v29, 0xffff0000, v92
	v_lshlrev_b32_e32 v30, 16, v93
	v_and_b32_e32 v31, 0xffff0000, v93
	v_pk_fma_f32 v[26:27], v[26:27], v[138:139], v[30:31]
	v_pk_fma_f32 v[24:25], v[24:25], v[136:137], v[28:29]
	flat_store_dwordx4 v[32:33], v[24:27] offset:64
	s_nop 1
	v_lshlrev_b32_e32 v24, 16, v94
	v_and_b32_e32 v25, 0xffff0000, v94
	v_lshlrev_b32_e32 v26, 16, v95
	v_and_b32_e32 v27, 0xffff0000, v95
	v_pk_fma_f32 v[22:23], v[22:23], v[134:135], v[26:27]
	v_pk_fma_f32 v[20:21], v[20:21], v[132:133], v[24:25]
	flat_store_dwordx4 v[32:33], v[20:23] offset:512
	s_nop 1
	v_lshlrev_b32_e32 v20, 16, v96
	v_and_b32_e32 v21, 0xffff0000, v96
	v_lshlrev_b32_e32 v22, 16, v97
	v_and_b32_e32 v23, 0xffff0000, v97
	v_pk_fma_f32 v[14:15], v[14:15], v[130:131], v[22:23]
	v_pk_fma_f32 v[12:13], v[12:13], v[128:129], v[20:21]
	flat_store_dwordx4 v[32:33], v[12:15] offset:576
	s_nop 1
	v_lshlrev_b32_e32 v12, 16, v100
	v_and_b32_e32 v13, 0xffff0000, v100
	v_pk_fma_f32 v[12:13], v[16:17], v[140:141], v[12:13]
	v_lshlrev_b64 v[16:17], 13, v[98:99]
	v_lshlrev_b32_e32 v14, 16, v101
	v_and_b32_e32 v15, 0xffff0000, v101
	v_lshl_add_u64 v[16:17], s[6:7], 0, v[16:17]
	v_pk_fma_f32 v[14:15], v[18:19], v[142:143], v[14:15]
	v_lshl_add_u64 v[16:17], v[16:17], 0, v[156:157]
	flat_store_dwordx4 v[16:17], v[12:15]
	s_nop 1
	v_lshlrev_b32_e32 v12, 16, v102
	v_and_b32_e32 v13, 0xffff0000, v102
	v_lshlrev_b32_e32 v14, 16, v103
	v_and_b32_e32 v15, 0xffff0000, v103
	v_pk_fma_f32 v[10:11], v[10:11], v[138:139], v[14:15]
	v_pk_fma_f32 v[8:9], v[8:9], v[136:137], v[12:13]
	flat_store_dwordx4 v[16:17], v[8:11] offset:64
	s_nop 1
	v_lshlrev_b32_e32 v8, 16, v66
	v_and_b32_e32 v9, 0xffff0000, v66
	v_lshlrev_b32_e32 v10, 16, v67
	v_and_b32_e32 v11, 0xffff0000, v67
	v_pk_fma_f32 v[6:7], v[6:7], v[134:135], v[10:11]
	v_pk_fma_f32 v[4:5], v[4:5], v[132:133], v[8:9]
	flat_store_dwordx4 v[16:17], v[4:7] offset:512
	s_nop 1
	v_lshlrev_b32_e32 v4, 16, v64
	v_and_b32_e32 v5, 0xffff0000, v64
	v_lshlrev_b32_e32 v6, 16, v65
	v_and_b32_e32 v7, 0xffff0000, v65
	v_pk_fma_f32 v[2:3], v[2:3], v[130:131], v[6:7]
	v_pk_fma_f32 v[0:1], v[0:1], v[128:129], v[4:5]
	flat_store_dwordx4 v[16:17], v[0:3] offset:576
	s_cbranch_vccnz .LBB0_1077
	s_andn2_b64 vcc, exec, s[12:13]
	s_cbranch_vccnz .LBB0_1076
	s_barrier
	s_branch .LBB0_1076
